# grid barrier: non-leader workgroups poll the top-level generation word directly instead of waiting for their XCD leader to republish it (one memory hop less per barrier)
# baseline (speedup 1.0000x reference)
.LBB0_40:
	s_or_b64 exec, exec, s[22:23]
	v_cvt_f32_u32_e32 v5, v3
	s_waitcnt vmcnt(0)
	v_readfirstlane_b32 s2, v4
	v_sub_u32_e32 v4, 0, v3
	v_rcp_iflag_f32_e32 v5, v5
	v_add_u32_e32 v6, s2, v2
	v_mul_f32_e32 v5, 0x4f7ffffe, v5
	v_cvt_u32_f32_e32 v5, v5
	v_mul_lo_u32 v2, v4, v5
	v_mul_hi_u32 v2, v5, v2
	v_add_u32_e32 v2, v5, v2
	v_mul_hi_u32 v2, v6, v2
	v_mul_lo_u32 v4, v2, v3
	v_sub_u32_e32 v4, v6, v4
	v_add_u32_e32 v5, 1, v2
	v_sub_u32_e32 v7, v4, v3
	v_cmp_ge_u32_e32 vcc, v4, v3
	s_nop 1
	v_cndmask_b32_e32 v2, v2, v5, vcc
	v_cndmask_b32_e32 v4, v4, v7, vcc
	v_add_u32_e32 v5, 1, v2
	v_cmp_ge_u32_e32 vcc, v4, v3
	v_add_u32_e32 v4, 1, v6
	s_nop 0
	v_cndmask_b32_e32 v2, v2, v5, vcc
	v_mul_lo_u32 v5, v3, v2
	v_add_u32_e32 v3, v5, v3
	v_cmp_ne_u32_e32 vcc, v4, v3
	s_and_saveexec_b64 s[22:23], vcc
	s_xor_b64 s[22:23], exec, s[22:23]
	s_cbranch_execz .LBB0_54
	v_readlane_b32 s4, v247, 50
	v_readlane_b32 s5, v247, 51
	s_waitcnt lgkmcnt(0)
	s_nop 3
	global_load_dword v1, v0, s[4:5] sc1
	s_waitcnt vmcnt(0)
	v_cmp_eq_u32_e32 vcc, v1, v2
	s_and_saveexec_b64 s[28:29], vcc
	s_cbranch_execz .LBB0_53
	s_mov_b32 s2, 1
	s_mov_b64 s[34:35], 0
	s_branch .LBB0_44

.LBB0_48:
	v_readlane_b32 s4, v247, 50
	v_readlane_b32 s5, v247, 51
	s_add_i32 s2, s2, 1
	s_mov_b64 s[40:41], -1
	s_nop 2
	global_load_dword v1, v0, s[4:5] sc1
	s_waitcnt vmcnt(0)
	v_cmp_ne_u32_e32 vcc, v1, v2
	s_orn2_b64 s[38:39], vcc, exec
	s_branch .LBB0_43
